# lean in-proj epilogue: next slab's LDS writes interleaved with this slab's convert+store groups (in-order LDS, counted lgkmcnt)
# speedup vs baseline: 1.0020x; 1.0020x over previous
.LBB0_220:
	s_cmp_gt_i32 s7, 0
	s_waitcnt vmcnt(6)
	s_cselect_b32 s8, -1, 2
	s_mul_i32 s9, s7, 0x6000
	s_waitcnt lgkmcnt(0)
	s_add_i32 s8, s8, s7
	v_add_u32_e32 v139, s9, v224
	v_add_u32_e32 v0, s9, v223
	s_mulk_i32 s8, 0x6000
	v_add_u32_e32 v154, v139, v228
	s_barrier
	v_lshl_add_u64 v[170:171], v[144:145], 0, s[2:3]
	v_add_u32_e32 v141, s8, v221
	v_lshl_add_u64 v[174:175], v[142:143], 0, s[2:3]
	v_add_u32_e32 v182, s8, v222
	v_add_u32_e32 v166, v0, v228
	ds_read_b128 v[146:149], v166
	ds_read_b128 v[150:153], v154
	ds_read_b128 v[154:157], v154 offset:2048
	v_lshl_add_u64 v[172:173], v[170:171], 0, s[88:89]
	v_lshl_add_u64 v[176:177], v[174:175], 0, s[88:89]
	v_add_u32_e32 v183, 0x4000, v182
	v_lshl_add_u64 v[178:179], v[170:171], 0, s[90:91]
	v_add_u32_e32 v184, 0x400, v141
	v_lshl_add_u64 v[180:181], v[170:171], 0, s[78:79]
	v_add_u32_e32 v185, 0x800, v141
	ds_read_b128 v[158:161], v166 offset:2048
	ds_read_b128 v[162:165], v166 offset:4096
	ds_read_b128 v[166:169], v166 offset:6144
	s_waitcnt lgkmcnt(3)
	s_setprio 1
	v_mfma_f32_32x32x16_bf16 v[114:129], v[146:149], v[150:153], v[114:129]
	v_mfma_f32_32x32x16_bf16 v[98:113], v[146:149], v[154:157], v[98:113]
	v_readfirstlane_b32 s8, v141
	s_mov_b32 m0, s8
	s_nop 0
	global_load_lds_dwordx4 v[172:173], off
	s_waitcnt lgkmcnt(2)
	v_mfma_f32_32x32x16_bf16 v[82:97], v[158:161], v[150:153], v[82:97]
	v_mfma_f32_32x32x16_bf16 v[66:81], v[158:161], v[154:157], v[66:81]
	v_readfirstlane_b32 s8, v184
	s_mov_b32 m0, s8
	s_nop 0
	global_load_lds_dwordx4 v[178:179], off
	s_waitcnt lgkmcnt(1)
	v_mfma_f32_32x32x16_bf16 v[50:65], v[162:165], v[150:153], v[50:65]
	v_mfma_f32_32x32x16_bf16 v[34:49], v[162:165], v[154:157], v[34:49]
	v_readfirstlane_b32 s8, v185
	s_mov_b32 m0, s8
	s_nop 0
	global_load_lds_dwordx4 v[180:181], off
	s_waitcnt lgkmcnt(0)
	v_mfma_f32_32x32x16_bf16 v[18:33], v[166:169], v[150:153], v[18:33]
	v_mfma_f32_32x32x16_bf16 v[2:17], v[166:169], v[154:157], v[2:17]
	s_setprio 0
	v_add_u32_e32 v0, v0, v229
	v_add_u32_e32 v139, v139, v229
	ds_read_b128 v[146:149], v0
	ds_read_b128 v[150:153], v139
	ds_read_b128 v[154:157], v139 offset:2048
	ds_read_b128 v[158:161], v0 offset:2048
	ds_read_b128 v[162:165], v0 offset:4096
	ds_read_b128 v[166:169], v0 offset:6144
	s_waitcnt lgkmcnt(3)
	s_setprio 1
	v_mfma_f32_32x32x16_bf16 v[114:129], v[146:149], v[150:153], v[114:129]
	v_mfma_f32_32x32x16_bf16 v[98:113], v[146:149], v[154:157], v[98:113]
	v_add_u32_e32 v0, 0xc00, v141
	v_lshl_add_u64 v[146:147], v[170:171], 0, s[76:77]
	v_readfirstlane_b32 s8, v0
	s_mov_b32 m0, s8
	s_nop 0
	global_load_lds_dwordx4 v[146:147], off
	s_waitcnt lgkmcnt(2)
	v_mfma_f32_32x32x16_bf16 v[82:97], v[158:161], v[150:153], v[82:97]
	v_mfma_f32_32x32x16_bf16 v[66:81], v[158:161], v[154:157], v[66:81]
	v_readfirstlane_b32 s8, v183
	s_mov_b32 m0, s8
	s_nop 0
	global_load_lds_dwordx4 v[176:177], off
	s_waitcnt lgkmcnt(1)
	v_mfma_f32_32x32x16_bf16 v[50:65], v[162:165], v[150:153], v[50:65]
	v_mfma_f32_32x32x16_bf16 v[34:49], v[162:165], v[154:157], v[34:49]
	v_add_u32_e32 v0, 0x4400, v182
	v_lshl_add_u64 v[146:147], v[174:175], 0, s[90:91]
	v_readfirstlane_b32 s8, v0
	s_mov_b32 m0, s8
	s_nop 0
	global_load_lds_dwordx4 v[146:147], off
	s_waitcnt lgkmcnt(0)
	v_mfma_f32_32x32x16_bf16 v[18:33], v[166:169], v[150:153], v[18:33]
	v_mfma_f32_32x32x16_bf16 v[2:17], v[166:169], v[154:157], v[2:17]
	s_setprio 0
	s_add_i32 s8, s7, 1
	s_cmp_lt_i32 s7, 2
	s_cselect_b32 s7, s8, 0
	s_add_u32 s2, s2, 0x80
	s_addc_u32 s3, s3, 0
	s_cmpk_eq_i32 s2, 0xf00
	s_cbranch_scc0 .LBB0_220
	s_waitcnt vmcnt(6)
	s_mul_i32 s2, s7, 0x6000
	s_waitcnt lgkmcnt(0)
	v_add_u32_e32 v139, s2, v224
	v_add_u32_e32 v0, s2, v223
	v_add_u32_e32 v150, v139, v228
	s_barrier
	v_add_u32_e32 v141, v0, v228
	ds_read_b128 v[142:145], v141
	ds_read_b128 v[146:149], v150
	ds_read_b128 v[150:153], v150 offset:2048
	ds_read_b128 v[154:157], v141 offset:2048
	ds_read_b128 v[158:161], v141 offset:4096
	ds_read_b128 v[162:165], v141 offset:6144
	s_waitcnt lgkmcnt(3)
	s_setprio 1
	v_mfma_f32_32x32x16_bf16 v[114:129], v[142:145], v[146:149], v[114:129]
	v_mfma_f32_32x32x16_bf16 v[98:113], v[142:145], v[150:153], v[98:113]
	s_waitcnt lgkmcnt(2)
	v_mfma_f32_32x32x16_bf16 v[82:97], v[154:157], v[146:149], v[82:97]
	v_mfma_f32_32x32x16_bf16 v[66:81], v[154:157], v[150:153], v[66:81]
	s_waitcnt lgkmcnt(1)
	v_mfma_f32_32x32x16_bf16 v[50:65], v[158:161], v[146:149], v[50:65]
	v_mfma_f32_32x32x16_bf16 v[34:49], v[158:161], v[150:153], v[34:49]
	s_waitcnt lgkmcnt(0)
	v_mfma_f32_32x32x16_bf16 v[18:33], v[162:165], v[146:149], v[18:33]
	v_mfma_f32_32x32x16_bf16 v[2:17], v[162:165], v[150:153], v[2:17]
	s_setprio 0
	v_add_u32_e32 v0, v0, v229
	v_add_u32_e32 v139, v139, v229
	ds_read_b128 v[142:145], v0
	ds_read_b128 v[146:149], v139
	ds_read_b128 v[150:153], v139 offset:2048
	ds_read_b128 v[154:157], v0 offset:2048
	ds_read_b128 v[158:161], v0 offset:4096
	ds_read_b128 v[162:165], v0 offset:6144
	s_waitcnt lgkmcnt(3)
	s_setprio 1
	v_mfma_f32_32x32x16_bf16 v[114:129], v[142:145], v[146:149], v[114:129]
	v_mfma_f32_32x32x16_bf16 v[98:113], v[142:145], v[150:153], v[98:113]
	s_waitcnt lgkmcnt(2)
	v_mfma_f32_32x32x16_bf16 v[82:97], v[154:157], v[146:149], v[82:97]
	v_mfma_f32_32x32x16_bf16 v[66:81], v[154:157], v[150:153], v[66:81]
	s_waitcnt lgkmcnt(1)
	v_mfma_f32_32x32x16_bf16 v[50:65], v[158:161], v[146:149], v[50:65]
	v_mfma_f32_32x32x16_bf16 v[34:49], v[158:161], v[150:153], v[34:49]
	s_waitcnt lgkmcnt(0)
	v_mfma_f32_32x32x16_bf16 v[18:33], v[162:165], v[146:149], v[18:33]
	v_mfma_f32_32x32x16_bf16 v[2:17], v[162:165], v[150:153], v[2:17]
	s_setprio 0
	s_waitcnt vmcnt(0)
	s_waitcnt lgkmcnt(0)
	s_barrier
	ds_read_b128 v[142:145], v232
	ds_read_b128 v[146:149], v233
	ds_read_b128 v[150:153], v233 offset:2048
	ds_read_b128 v[154:157], v232 offset:2048
	ds_read_b128 v[158:161], v232 offset:4096
	ds_read_b128 v[162:165], v232 offset:6144
	s_waitcnt lgkmcnt(3)
	s_setprio 1
	v_mfma_f32_32x32x16_bf16 v[114:129], v[142:145], v[146:149], v[114:129]
	v_mfma_f32_32x32x16_bf16 v[98:113], v[142:145], v[150:153], v[98:113]
	s_waitcnt lgkmcnt(2)
	v_mfma_f32_32x32x16_bf16 v[82:97], v[154:157], v[146:149], v[82:97]
	v_mfma_f32_32x32x16_bf16 v[66:81], v[154:157], v[150:153], v[66:81]
	s_waitcnt lgkmcnt(1)
	v_mfma_f32_32x32x16_bf16 v[50:65], v[158:161], v[146:149], v[50:65]
	v_mfma_f32_32x32x16_bf16 v[34:49], v[158:161], v[150:153], v[34:49]
	s_waitcnt lgkmcnt(0)
	v_mfma_f32_32x32x16_bf16 v[18:33], v[162:165], v[146:149], v[18:33]
	v_mfma_f32_32x32x16_bf16 v[2:17], v[162:165], v[150:153], v[2:17]
	s_setprio 0
	ds_read_b128 v[142:145], v234
	ds_read_b128 v[146:149], v235
	ds_read_b128 v[150:153], v235 offset:2048
	ds_read_b128 v[154:157], v234 offset:2048
	ds_read_b128 v[158:161], v234 offset:4096
	ds_read_b128 v[162:165], v234 offset:6144
	s_waitcnt lgkmcnt(3)
	s_setprio 1
	v_mfma_f32_32x32x16_bf16 v[114:129], v[142:145], v[146:149], v[114:129]
	v_mfma_f32_32x32x16_bf16 v[98:113], v[142:145], v[150:153], v[98:113]
	s_waitcnt lgkmcnt(2)
	v_mfma_f32_32x32x16_bf16 v[82:97], v[154:157], v[146:149], v[82:97]
	v_mfma_f32_32x32x16_bf16 v[66:81], v[154:157], v[150:153], v[66:81]
	s_waitcnt lgkmcnt(1)
	v_mfma_f32_32x32x16_bf16 v[50:65], v[158:161], v[146:149], v[50:65]
	v_mfma_f32_32x32x16_bf16 v[34:49], v[158:161], v[150:153], v[34:49]
	s_waitcnt lgkmcnt(0)
	v_mfma_f32_32x32x16_bf16 v[18:33], v[162:165], v[146:149], v[18:33]
	v_mfma_f32_32x32x16_bf16 v[2:17], v[162:165], v[150:153], v[2:17]
	s_setprio 0
	s_cmp_gt_i32 s4, 3
	s_cselect_b64 s[30:31], -1, 0
	s_add_i32 s2, s4, -8
	s_cmp_gt_u32 s2, 5
	s_cselect_b64 s[98:99], -1, 0
	s_and_b32 s2, s4, 0x7ffffffc
	s_cmp_lg_u32 s2, 20
	v_add_u32_e32 v238, s5, v225
	s_cselect_b64 s[2:3], -1, 0
	s_and_b32 s5, s4, 0x7ffffffe
	s_cmp_eq_u32 s5, 6
	s_cselect_b64 s[82:83], -1, 0
	s_sub_i32 s5, s4, 17
	v_add_u32_e32 v239, 0x800, v230
	v_add_u32_e32 v240, 0x1000, v230
	v_add_u32_e32 v241, 0x1800, v230
	s_mov_b32 s8, 0x0701c030
	s_mov_b32 s34, 0x380e00c0
	s_lshr_b32 s8, s8, s4
	s_lshr_b32 s34, s34, s4
	s_and_b32 s8, s8, 1
	s_and_b32 s34, s34, 1
	s_or_b32 s7, s8, s34
	s_cmp_eq_u32 s7, 0
	s_cbranch_scc1 .Lmy_g0e_std
	v_and_b32_e32 v151, 63, v200
	v_lshrrev_b32_e32 v150, 5, v151
	v_and_b32_e32 v146, 31, v151
	v_lshrrev_b32_e32 v147, 6, v200
	v_lshrrev_b32_e32 v152, 1, v147
	v_and_b32_e32 v148, 1, v147
	v_mul_u32_u24_e32 v147, 0x2200, v147
	s_movk_i32 s6, 0x7c00
	v_mad_u32_u24 v147, v152, s6, v147
	v_lshlrev_b32_e32 v146, 2, v146
	s_movk_i32 s6, 0x440
	v_mad_u32_u24 v146, v150, s6, v146
	v_add_u32_e32 v146, v146, v147
	v_lshrrev_b32_e32 v150, 3, v151
	v_and_b32_e32 v149, 7, v151
	s_movk_i32 s6, 0x110
	v_mad_u32_u24 v147, v150, s6, v147
	v_lshl_add_u32 v147, v149, 5, v147
	v_lshl_add_u32 v152, v152, 7, s32
	v_add_u32_e32 v152, v152, v150
	s_lshl_b32 s6, s4, 7
	v_lshl_add_u32 v148, v148, 6, s6
	v_lshl_add_u32 v148, v149, 3, v148
	v_lshlrev_b32_e32 v148, 1, v148
	v_mul_u32_u24_e32 v152, 0x1e00, v152
	v_add_u32_e32 v148, v148, v152
	s_mov_b64 s[8:9], s[64:65]
	s_cmp_eq_u32 s34, 1
	s_cbranch_scc1 .Lmy_g0e_gate
	ds_write2_b32 v146, v114, v98 offset0:0 offset1:32
	ds_write2_b32 v146, v115, v99 offset0:68 offset1:100
	ds_write2_b32 v146, v116, v100 offset0:136 offset1:168
	ds_write2_b32 v146, v117, v101 offset0:204 offset1:236
	v_add_u32_e32 v146, 0x880, v146
	ds_write2_b32 v146, v118, v102 offset0:0 offset1:32
	ds_write2_b32 v146, v119, v103 offset0:68 offset1:100
	ds_write2_b32 v146, v120, v104 offset0:136 offset1:168
	ds_write2_b32 v146, v121, v105 offset0:204 offset1:236
	v_add_u32_e32 v146, 0x880, v146
	ds_write2_b32 v146, v122, v106 offset0:0 offset1:32
	ds_write2_b32 v146, v123, v107 offset0:68 offset1:100
	ds_write2_b32 v146, v124, v108 offset0:136 offset1:168
	ds_write2_b32 v146, v125, v109 offset0:204 offset1:236
	v_add_u32_e32 v146, 0x880, v146
	ds_write2_b32 v146, v126, v110 offset0:0 offset1:32
	ds_write2_b32 v146, v127, v111 offset0:68 offset1:100
	ds_write2_b32 v146, v128, v112 offset0:136 offset1:168
	ds_write2_b32 v146, v129, v113 offset0:204 offset1:236
	v_subrev_u32_e32 v146, 0x1980, v146
	ds_read_b128 v[98:101], v147
	ds_read_b128 v[102:105], v147 offset:16
	ds_read_b128 v[106:109], v147 offset:2176
	ds_read_b128 v[110:113], v147 offset:2192
	ds_read_b128 v[114:117], v147 offset:4352
	ds_read_b128 v[118:121], v147 offset:4368
	ds_read_b128 v[122:125], v147 offset:6528
	ds_read_b128 v[126:129], v147 offset:6544
	s_waitcnt lgkmcnt(6)
	v_cvt_pk_bf16_f32 v154, v98, v99
	v_cvt_pk_bf16_f32 v155, v100, v101
	v_cvt_pk_bf16_f32 v156, v102, v103
	v_cvt_pk_bf16_f32 v157, v104, v105
	global_store_dwordx4 v148, v[154:157], s[8:9]
	s_add_u32 s8, s8, 0xf000
	s_addc_u32 s9, s9, 0
	ds_write2_b32 v146, v82, v66 offset0:0 offset1:32
	ds_write2_b32 v146, v83, v67 offset0:68 offset1:100
	ds_write2_b32 v146, v84, v68 offset0:136 offset1:168
	ds_write2_b32 v146, v85, v69 offset0:204 offset1:236
	v_add_u32_e32 v146, 0x880, v146
	s_waitcnt lgkmcnt(8)
	v_cvt_pk_bf16_f32 v158, v106, v107
	v_cvt_pk_bf16_f32 v159, v108, v109
	v_cvt_pk_bf16_f32 v160, v110, v111
	v_cvt_pk_bf16_f32 v161, v112, v113
	global_store_dwordx4 v148, v[158:161], s[8:9]
	s_add_u32 s8, s8, 0xf000
	s_addc_u32 s9, s9, 0
	ds_write2_b32 v146, v86, v70 offset0:0 offset1:32
	ds_write2_b32 v146, v87, v71 offset0:68 offset1:100
	ds_write2_b32 v146, v88, v72 offset0:136 offset1:168
	ds_write2_b32 v146, v89, v73 offset0:204 offset1:236
	v_add_u32_e32 v146, 0x880, v146
	s_waitcnt lgkmcnt(10)
	v_cvt_pk_bf16_f32 v162, v114, v115
	v_cvt_pk_bf16_f32 v163, v116, v117
	v_cvt_pk_bf16_f32 v164, v118, v119
	v_cvt_pk_bf16_f32 v165, v120, v121
	global_store_dwordx4 v148, v[162:165], s[8:9]
	s_add_u32 s8, s8, 0xf000
	s_addc_u32 s9, s9, 0
	ds_write2_b32 v146, v90, v74 offset0:0 offset1:32
	ds_write2_b32 v146, v91, v75 offset0:68 offset1:100
	ds_write2_b32 v146, v92, v76 offset0:136 offset1:168
	ds_write2_b32 v146, v93, v77 offset0:204 offset1:236
	v_add_u32_e32 v146, 0x880, v146
	s_waitcnt lgkmcnt(12)
	v_cvt_pk_bf16_f32 v166, v122, v123
	v_cvt_pk_bf16_f32 v167, v124, v125
	v_cvt_pk_bf16_f32 v168, v126, v127
	v_cvt_pk_bf16_f32 v169, v128, v129
	global_store_dwordx4 v148, v[166:169], s[8:9]
	s_add_u32 s8, s8, 0xf000
	s_addc_u32 s9, s9, 0
	ds_write2_b32 v146, v94, v78 offset0:0 offset1:32
	ds_write2_b32 v146, v95, v79 offset0:68 offset1:100
	ds_write2_b32 v146, v96, v80 offset0:136 offset1:168
	ds_write2_b32 v146, v97, v81 offset0:204 offset1:236
	v_subrev_u32_e32 v146, 0x1980, v146
	ds_read_b128 v[66:69], v147
	ds_read_b128 v[70:73], v147 offset:16
	ds_read_b128 v[74:77], v147 offset:2176
	ds_read_b128 v[78:81], v147 offset:2192
	ds_read_b128 v[82:85], v147 offset:4352
	ds_read_b128 v[86:89], v147 offset:4368
	ds_read_b128 v[90:93], v147 offset:6528
	ds_read_b128 v[94:97], v147 offset:6544
	s_waitcnt lgkmcnt(6)
	v_cvt_pk_bf16_f32 v154, v66, v67
	v_cvt_pk_bf16_f32 v155, v68, v69
	v_cvt_pk_bf16_f32 v156, v70, v71
	v_cvt_pk_bf16_f32 v157, v72, v73
	global_store_dwordx4 v148, v[154:157], s[8:9]
	s_add_u32 s8, s8, 0xf000
	s_addc_u32 s9, s9, 0
	ds_write2_b32 v146, v50, v34 offset0:0 offset1:32
	ds_write2_b32 v146, v51, v35 offset0:68 offset1:100
	ds_write2_b32 v146, v52, v36 offset0:136 offset1:168
	ds_write2_b32 v146, v53, v37 offset0:204 offset1:236
	v_add_u32_e32 v146, 0x880, v146
	s_waitcnt lgkmcnt(8)
	v_cvt_pk_bf16_f32 v158, v74, v75
	v_cvt_pk_bf16_f32 v159, v76, v77
	v_cvt_pk_bf16_f32 v160, v78, v79
	v_cvt_pk_bf16_f32 v161, v80, v81
	global_store_dwordx4 v148, v[158:161], s[8:9]
	s_add_u32 s8, s8, 0xf000
	s_addc_u32 s9, s9, 0
	ds_write2_b32 v146, v54, v38 offset0:0 offset1:32
	ds_write2_b32 v146, v55, v39 offset0:68 offset1:100
	ds_write2_b32 v146, v56, v40 offset0:136 offset1:168
	ds_write2_b32 v146, v57, v41 offset0:204 offset1:236
	v_add_u32_e32 v146, 0x880, v146
	s_waitcnt lgkmcnt(10)
	v_cvt_pk_bf16_f32 v162, v82, v83
	v_cvt_pk_bf16_f32 v163, v84, v85
	v_cvt_pk_bf16_f32 v164, v86, v87
	v_cvt_pk_bf16_f32 v165, v88, v89
	global_store_dwordx4 v148, v[162:165], s[8:9]
	s_add_u32 s8, s8, 0xf000
	s_addc_u32 s9, s9, 0
	ds_write2_b32 v146, v58, v42 offset0:0 offset1:32
	ds_write2_b32 v146, v59, v43 offset0:68 offset1:100
	ds_write2_b32 v146, v60, v44 offset0:136 offset1:168
	ds_write2_b32 v146, v61, v45 offset0:204 offset1:236
	v_add_u32_e32 v146, 0x880, v146
	s_waitcnt lgkmcnt(12)
	v_cvt_pk_bf16_f32 v166, v90, v91
	v_cvt_pk_bf16_f32 v167, v92, v93
	v_cvt_pk_bf16_f32 v168, v94, v95
	v_cvt_pk_bf16_f32 v169, v96, v97
	global_store_dwordx4 v148, v[166:169], s[8:9]
	s_add_u32 s8, s8, 0xf000
	s_addc_u32 s9, s9, 0
	ds_write2_b32 v146, v62, v46 offset0:0 offset1:32
	ds_write2_b32 v146, v63, v47 offset0:68 offset1:100
	ds_write2_b32 v146, v64, v48 offset0:136 offset1:168
	ds_write2_b32 v146, v65, v49 offset0:204 offset1:236
	v_subrev_u32_e32 v146, 0x1980, v146
	ds_read_b128 v[34:37], v147
	ds_read_b128 v[38:41], v147 offset:16
	ds_read_b128 v[42:45], v147 offset:2176
	ds_read_b128 v[46:49], v147 offset:2192
	ds_read_b128 v[50:53], v147 offset:4352
	ds_read_b128 v[54:57], v147 offset:4368
	ds_read_b128 v[58:61], v147 offset:6528
	ds_read_b128 v[62:65], v147 offset:6544
	s_waitcnt lgkmcnt(6)
	v_cvt_pk_bf16_f32 v154, v34, v35
	v_cvt_pk_bf16_f32 v155, v36, v37
	v_cvt_pk_bf16_f32 v156, v38, v39
	v_cvt_pk_bf16_f32 v157, v40, v41
	global_store_dwordx4 v148, v[154:157], s[8:9]
	s_add_u32 s8, s8, 0xf000
	s_addc_u32 s9, s9, 0
	ds_write2_b32 v146, v18, v2 offset0:0 offset1:32
	ds_write2_b32 v146, v19, v3 offset0:68 offset1:100
	ds_write2_b32 v146, v20, v4 offset0:136 offset1:168
	ds_write2_b32 v146, v21, v5 offset0:204 offset1:236
	v_add_u32_e32 v146, 0x880, v146
	s_waitcnt lgkmcnt(8)
	v_cvt_pk_bf16_f32 v158, v42, v43
	v_cvt_pk_bf16_f32 v159, v44, v45
	v_cvt_pk_bf16_f32 v160, v46, v47
	v_cvt_pk_bf16_f32 v161, v48, v49
	global_store_dwordx4 v148, v[158:161], s[8:9]
	s_add_u32 s8, s8, 0xf000
	s_addc_u32 s9, s9, 0
	ds_write2_b32 v146, v22, v6 offset0:0 offset1:32
	ds_write2_b32 v146, v23, v7 offset0:68 offset1:100
	ds_write2_b32 v146, v24, v8 offset0:136 offset1:168
	ds_write2_b32 v146, v25, v9 offset0:204 offset1:236
	v_add_u32_e32 v146, 0x880, v146
	s_waitcnt lgkmcnt(10)
	v_cvt_pk_bf16_f32 v162, v50, v51
	v_cvt_pk_bf16_f32 v163, v52, v53
	v_cvt_pk_bf16_f32 v164, v54, v55
	v_cvt_pk_bf16_f32 v165, v56, v57
	global_store_dwordx4 v148, v[162:165], s[8:9]
	s_add_u32 s8, s8, 0xf000
	s_addc_u32 s9, s9, 0
	ds_write2_b32 v146, v26, v10 offset0:0 offset1:32
	ds_write2_b32 v146, v27, v11 offset0:68 offset1:100
	ds_write2_b32 v146, v28, v12 offset0:136 offset1:168
	ds_write2_b32 v146, v29, v13 offset0:204 offset1:236
	v_add_u32_e32 v146, 0x880, v146
	s_waitcnt lgkmcnt(12)
	v_cvt_pk_bf16_f32 v166, v58, v59
	v_cvt_pk_bf16_f32 v167, v60, v61
	v_cvt_pk_bf16_f32 v168, v62, v63
	v_cvt_pk_bf16_f32 v169, v64, v65
	global_store_dwordx4 v148, v[166:169], s[8:9]
	s_add_u32 s8, s8, 0xf000
	s_addc_u32 s9, s9, 0
	ds_write2_b32 v146, v30, v14 offset0:0 offset1:32
	ds_write2_b32 v146, v31, v15 offset0:68 offset1:100
	ds_write2_b32 v146, v32, v16 offset0:136 offset1:168
	ds_write2_b32 v146, v33, v17 offset0:204 offset1:236
	v_subrev_u32_e32 v146, 0x1980, v146
	ds_read_b128 v[2:5], v147
	ds_read_b128 v[6:9], v147 offset:16
	ds_read_b128 v[10:13], v147 offset:2176
	ds_read_b128 v[14:17], v147 offset:2192
	ds_read_b128 v[18:21], v147 offset:4352
	ds_read_b128 v[22:25], v147 offset:4368
	ds_read_b128 v[26:29], v147 offset:6528
	ds_read_b128 v[30:33], v147 offset:6544
	s_waitcnt lgkmcnt(0)
	s_barrier
	v_cvt_pk_bf16_f32 v154, v2, v3
	v_cvt_pk_bf16_f32 v155, v4, v5
	v_cvt_pk_bf16_f32 v156, v6, v7
	v_cvt_pk_bf16_f32 v157, v8, v9
	global_store_dwordx4 v148, v[154:157], s[8:9]
	s_add_u32 s8, s8, 0xf000
	s_addc_u32 s9, s9, 0
	v_cvt_pk_bf16_f32 v158, v10, v11
	v_cvt_pk_bf16_f32 v159, v12, v13
	v_cvt_pk_bf16_f32 v160, v14, v15
	v_cvt_pk_bf16_f32 v161, v16, v17
	global_store_dwordx4 v148, v[158:161], s[8:9]
	s_add_u32 s8, s8, 0xf000
	s_addc_u32 s9, s9, 0
	v_cvt_pk_bf16_f32 v162, v18, v19
	v_cvt_pk_bf16_f32 v163, v20, v21
	v_cvt_pk_bf16_f32 v164, v22, v23
	v_cvt_pk_bf16_f32 v165, v24, v25
	global_store_dwordx4 v148, v[162:165], s[8:9]
	s_add_u32 s8, s8, 0xf000
	s_addc_u32 s9, s9, 0
	v_cvt_pk_bf16_f32 v166, v26, v27
	v_cvt_pk_bf16_f32 v167, v28, v29
	v_cvt_pk_bf16_f32 v168, v30, v31
	v_cvt_pk_bf16_f32 v169, v32, v33
	global_store_dwordx4 v148, v[166:169], s[8:9]
	s_add_u32 s8, s8, 0xf000
	s_addc_u32 s9, s9, 0
	s_add_i32 s70, s70, s10
	s_cmp_lt_i32 s70, s71
	s_cbranch_scc0 .LBB0_209
	s_branch .LBB0_215
.Lmy_g0e_gate:
	ds_write2_b32 v146, v114, v98 offset0:0 offset1:32
	ds_write2_b32 v146, v115, v99 offset0:68 offset1:100
	ds_write2_b32 v146, v116, v100 offset0:136 offset1:168
	ds_write2_b32 v146, v117, v101 offset0:204 offset1:236
	v_add_u32_e32 v146, 0x880, v146
	ds_write2_b32 v146, v118, v102 offset0:0 offset1:32
	ds_write2_b32 v146, v119, v103 offset0:68 offset1:100
	ds_write2_b32 v146, v120, v104 offset0:136 offset1:168
	ds_write2_b32 v146, v121, v105 offset0:204 offset1:236
	v_add_u32_e32 v146, 0x880, v146
	ds_write2_b32 v146, v122, v106 offset0:0 offset1:32
	ds_write2_b32 v146, v123, v107 offset0:68 offset1:100
	ds_write2_b32 v146, v124, v108 offset0:136 offset1:168
	ds_write2_b32 v146, v125, v109 offset0:204 offset1:236
	v_add_u32_e32 v146, 0x880, v146
	ds_write2_b32 v146, v126, v110 offset0:0 offset1:32
	ds_write2_b32 v146, v127, v111 offset0:68 offset1:100
	ds_write2_b32 v146, v128, v112 offset0:136 offset1:168
	ds_write2_b32 v146, v129, v113 offset0:204 offset1:236
	v_subrev_u32_e32 v146, 0x1980, v146
	ds_read_b128 v[98:101], v147
	ds_read_b128 v[102:105], v147 offset:16
	ds_read_b128 v[106:109], v147 offset:2176
	ds_read_b128 v[110:113], v147 offset:2192
	ds_read_b128 v[114:117], v147 offset:4352
	ds_read_b128 v[118:121], v147 offset:4368
	ds_read_b128 v[122:125], v147 offset:6528
	ds_read_b128 v[126:129], v147 offset:6544
	s_waitcnt lgkmcnt(6)
	v_mul_f32_e32 v170, 0xbfb8aa3b, v98
	v_mul_f32_e32 v171, 0xbfb8aa3b, v99
	v_mul_f32_e32 v172, 0xbfb8aa3b, v100
	v_mul_f32_e32 v173, 0xbfb8aa3b, v101
	v_exp_f32_e32 v170, v170
	v_exp_f32_e32 v171, v171
	v_exp_f32_e32 v172, v172
	v_exp_f32_e32 v173, v173
	v_add_f32_e32 v170, 1.0, v170
	v_add_f32_e32 v171, 1.0, v171
	v_add_f32_e32 v172, 1.0, v172
	v_add_f32_e32 v173, 1.0, v173
	v_rcp_f32_e32 v170, v170
	v_rcp_f32_e32 v171, v171
	v_rcp_f32_e32 v172, v172
	v_rcp_f32_e32 v173, v173
	s_nop 0
	v_mul_f32_e32 v98, v98, v170
	v_mul_f32_e32 v99, v99, v171
	v_mul_f32_e32 v100, v100, v172
	v_mul_f32_e32 v101, v101, v173
	v_cvt_pk_bf16_f32 v154, v98, v99
	v_cvt_pk_bf16_f32 v155, v100, v101
	v_mul_f32_e32 v170, 0xbfb8aa3b, v102
	v_mul_f32_e32 v171, 0xbfb8aa3b, v103
	v_mul_f32_e32 v172, 0xbfb8aa3b, v104
	v_mul_f32_e32 v173, 0xbfb8aa3b, v105
	v_exp_f32_e32 v170, v170
	v_exp_f32_e32 v171, v171
	v_exp_f32_e32 v172, v172
	v_exp_f32_e32 v173, v173
	v_add_f32_e32 v170, 1.0, v170
	v_add_f32_e32 v171, 1.0, v171
	v_add_f32_e32 v172, 1.0, v172
	v_add_f32_e32 v173, 1.0, v173
	v_rcp_f32_e32 v170, v170
	v_rcp_f32_e32 v171, v171
	v_rcp_f32_e32 v172, v172
	v_rcp_f32_e32 v173, v173
	s_nop 0
	v_mul_f32_e32 v102, v102, v170
	v_mul_f32_e32 v103, v103, v171
	v_mul_f32_e32 v104, v104, v172
	v_mul_f32_e32 v105, v105, v173
	v_cvt_pk_bf16_f32 v156, v102, v103
	v_cvt_pk_bf16_f32 v157, v104, v105
	global_store_dwordx4 v148, v[154:157], s[8:9]
	s_add_u32 s8, s8, 0xf000
	s_addc_u32 s9, s9, 0
	ds_write2_b32 v146, v82, v66 offset0:0 offset1:32
	ds_write2_b32 v146, v83, v67 offset0:68 offset1:100
	ds_write2_b32 v146, v84, v68 offset0:136 offset1:168
	ds_write2_b32 v146, v85, v69 offset0:204 offset1:236
	v_add_u32_e32 v146, 0x880, v146
	s_waitcnt lgkmcnt(8)
	v_mul_f32_e32 v170, 0xbfb8aa3b, v106
	v_mul_f32_e32 v171, 0xbfb8aa3b, v107
	v_mul_f32_e32 v172, 0xbfb8aa3b, v108
	v_mul_f32_e32 v173, 0xbfb8aa3b, v109
	v_exp_f32_e32 v170, v170
	v_exp_f32_e32 v171, v171
	v_exp_f32_e32 v172, v172
	v_exp_f32_e32 v173, v173
	v_add_f32_e32 v170, 1.0, v170
	v_add_f32_e32 v171, 1.0, v171
	v_add_f32_e32 v172, 1.0, v172
	v_add_f32_e32 v173, 1.0, v173
	v_rcp_f32_e32 v170, v170
	v_rcp_f32_e32 v171, v171
	v_rcp_f32_e32 v172, v172
	v_rcp_f32_e32 v173, v173
	s_nop 0
	v_mul_f32_e32 v106, v106, v170
	v_mul_f32_e32 v107, v107, v171
	v_mul_f32_e32 v108, v108, v172
	v_mul_f32_e32 v109, v109, v173
	v_cvt_pk_bf16_f32 v158, v106, v107
	v_cvt_pk_bf16_f32 v159, v108, v109
	v_mul_f32_e32 v170, 0xbfb8aa3b, v110
	v_mul_f32_e32 v171, 0xbfb8aa3b, v111
	v_mul_f32_e32 v172, 0xbfb8aa3b, v112
	v_mul_f32_e32 v173, 0xbfb8aa3b, v113
	v_exp_f32_e32 v170, v170
	v_exp_f32_e32 v171, v171
	v_exp_f32_e32 v172, v172
	v_exp_f32_e32 v173, v173
	v_add_f32_e32 v170, 1.0, v170
	v_add_f32_e32 v171, 1.0, v171
	v_add_f32_e32 v172, 1.0, v172
	v_add_f32_e32 v173, 1.0, v173
	v_rcp_f32_e32 v170, v170
	v_rcp_f32_e32 v171, v171
	v_rcp_f32_e32 v172, v172
	v_rcp_f32_e32 v173, v173
	s_nop 0
	v_mul_f32_e32 v110, v110, v170
	v_mul_f32_e32 v111, v111, v171
	v_mul_f32_e32 v112, v112, v172
	v_mul_f32_e32 v113, v113, v173
	v_cvt_pk_bf16_f32 v160, v110, v111
	v_cvt_pk_bf16_f32 v161, v112, v113
	global_store_dwordx4 v148, v[158:161], s[8:9]
	s_add_u32 s8, s8, 0xf000
	s_addc_u32 s9, s9, 0
	ds_write2_b32 v146, v86, v70 offset0:0 offset1:32
	ds_write2_b32 v146, v87, v71 offset0:68 offset1:100
	ds_write2_b32 v146, v88, v72 offset0:136 offset1:168
	ds_write2_b32 v146, v89, v73 offset0:204 offset1:236
	v_add_u32_e32 v146, 0x880, v146
	s_waitcnt lgkmcnt(10)
	v_mul_f32_e32 v170, 0xbfb8aa3b, v114
	v_mul_f32_e32 v171, 0xbfb8aa3b, v115
	v_mul_f32_e32 v172, 0xbfb8aa3b, v116
	v_mul_f32_e32 v173, 0xbfb8aa3b, v117
	v_exp_f32_e32 v170, v170
	v_exp_f32_e32 v171, v171
	v_exp_f32_e32 v172, v172
	v_exp_f32_e32 v173, v173
	v_add_f32_e32 v170, 1.0, v170
	v_add_f32_e32 v171, 1.0, v171
	v_add_f32_e32 v172, 1.0, v172
	v_add_f32_e32 v173, 1.0, v173
	v_rcp_f32_e32 v170, v170
	v_rcp_f32_e32 v171, v171
	v_rcp_f32_e32 v172, v172
	v_rcp_f32_e32 v173, v173
	s_nop 0
	v_mul_f32_e32 v114, v114, v170
	v_mul_f32_e32 v115, v115, v171
	v_mul_f32_e32 v116, v116, v172
	v_mul_f32_e32 v117, v117, v173
	v_cvt_pk_bf16_f32 v162, v114, v115
	v_cvt_pk_bf16_f32 v163, v116, v117
	v_mul_f32_e32 v170, 0xbfb8aa3b, v118
	v_mul_f32_e32 v171, 0xbfb8aa3b, v119
	v_mul_f32_e32 v172, 0xbfb8aa3b, v120
	v_mul_f32_e32 v173, 0xbfb8aa3b, v121
	v_exp_f32_e32 v170, v170
	v_exp_f32_e32 v171, v171
	v_exp_f32_e32 v172, v172
	v_exp_f32_e32 v173, v173
	v_add_f32_e32 v170, 1.0, v170
	v_add_f32_e32 v171, 1.0, v171
	v_add_f32_e32 v172, 1.0, v172
	v_add_f32_e32 v173, 1.0, v173
	v_rcp_f32_e32 v170, v170
	v_rcp_f32_e32 v171, v171
	v_rcp_f32_e32 v172, v172
	v_rcp_f32_e32 v173, v173
	s_nop 0
	v_mul_f32_e32 v118, v118, v170
	v_mul_f32_e32 v119, v119, v171
	v_mul_f32_e32 v120, v120, v172
	v_mul_f32_e32 v121, v121, v173
	v_cvt_pk_bf16_f32 v164, v118, v119
	v_cvt_pk_bf16_f32 v165, v120, v121
	global_store_dwordx4 v148, v[162:165], s[8:9]
	s_add_u32 s8, s8, 0xf000
	s_addc_u32 s9, s9, 0
	ds_write2_b32 v146, v90, v74 offset0:0 offset1:32
	ds_write2_b32 v146, v91, v75 offset0:68 offset1:100
	ds_write2_b32 v146, v92, v76 offset0:136 offset1:168
	ds_write2_b32 v146, v93, v77 offset0:204 offset1:236
	v_add_u32_e32 v146, 0x880, v146
	s_waitcnt lgkmcnt(12)
	v_mul_f32_e32 v170, 0xbfb8aa3b, v122
	v_mul_f32_e32 v171, 0xbfb8aa3b, v123
	v_mul_f32_e32 v172, 0xbfb8aa3b, v124
	v_mul_f32_e32 v173, 0xbfb8aa3b, v125
	v_exp_f32_e32 v170, v170
	v_exp_f32_e32 v171, v171
	v_exp_f32_e32 v172, v172
	v_exp_f32_e32 v173, v173
	v_add_f32_e32 v170, 1.0, v170
	v_add_f32_e32 v171, 1.0, v171
	v_add_f32_e32 v172, 1.0, v172
	v_add_f32_e32 v173, 1.0, v173
	v_rcp_f32_e32 v170, v170
	v_rcp_f32_e32 v171, v171
	v_rcp_f32_e32 v172, v172
	v_rcp_f32_e32 v173, v173
	s_nop 0
	v_mul_f32_e32 v122, v122, v170
	v_mul_f32_e32 v123, v123, v171
	v_mul_f32_e32 v124, v124, v172
	v_mul_f32_e32 v125, v125, v173
	v_cvt_pk_bf16_f32 v166, v122, v123
	v_cvt_pk_bf16_f32 v167, v124, v125
	v_mul_f32_e32 v170, 0xbfb8aa3b, v126
	v_mul_f32_e32 v171, 0xbfb8aa3b, v127
	v_mul_f32_e32 v172, 0xbfb8aa3b, v128
	v_mul_f32_e32 v173, 0xbfb8aa3b, v129
	v_exp_f32_e32 v170, v170
	v_exp_f32_e32 v171, v171
	v_exp_f32_e32 v172, v172
	v_exp_f32_e32 v173, v173
	v_add_f32_e32 v170, 1.0, v170
	v_add_f32_e32 v171, 1.0, v171
	v_add_f32_e32 v172, 1.0, v172
	v_add_f32_e32 v173, 1.0, v173
	v_rcp_f32_e32 v170, v170
	v_rcp_f32_e32 v171, v171
	v_rcp_f32_e32 v172, v172
	v_rcp_f32_e32 v173, v173
	s_nop 0
	v_mul_f32_e32 v126, v126, v170
	v_mul_f32_e32 v127, v127, v171
	v_mul_f32_e32 v128, v128, v172
	v_mul_f32_e32 v129, v129, v173
	v_cvt_pk_bf16_f32 v168, v126, v127
	v_cvt_pk_bf16_f32 v169, v128, v129
	global_store_dwordx4 v148, v[166:169], s[8:9]
	s_add_u32 s8, s8, 0xf000
	s_addc_u32 s9, s9, 0
	ds_write2_b32 v146, v94, v78 offset0:0 offset1:32
	ds_write2_b32 v146, v95, v79 offset0:68 offset1:100
	ds_write2_b32 v146, v96, v80 offset0:136 offset1:168
	ds_write2_b32 v146, v97, v81 offset0:204 offset1:236
	v_subrev_u32_e32 v146, 0x1980, v146
	ds_read_b128 v[66:69], v147
	ds_read_b128 v[70:73], v147 offset:16
	ds_read_b128 v[74:77], v147 offset:2176
	ds_read_b128 v[78:81], v147 offset:2192
	ds_read_b128 v[82:85], v147 offset:4352
	ds_read_b128 v[86:89], v147 offset:4368
	ds_read_b128 v[90:93], v147 offset:6528
	ds_read_b128 v[94:97], v147 offset:6544
	s_waitcnt lgkmcnt(6)
	v_mul_f32_e32 v170, 0xbfb8aa3b, v66
	v_mul_f32_e32 v171, 0xbfb8aa3b, v67
	v_mul_f32_e32 v172, 0xbfb8aa3b, v68
	v_mul_f32_e32 v173, 0xbfb8aa3b, v69
	v_exp_f32_e32 v170, v170
	v_exp_f32_e32 v171, v171
	v_exp_f32_e32 v172, v172
	v_exp_f32_e32 v173, v173
	v_add_f32_e32 v170, 1.0, v170
	v_add_f32_e32 v171, 1.0, v171
	v_add_f32_e32 v172, 1.0, v172
	v_add_f32_e32 v173, 1.0, v173
	v_rcp_f32_e32 v170, v170
	v_rcp_f32_e32 v171, v171
	v_rcp_f32_e32 v172, v172
	v_rcp_f32_e32 v173, v173
	s_nop 0
	v_mul_f32_e32 v66, v66, v170
	v_mul_f32_e32 v67, v67, v171
	v_mul_f32_e32 v68, v68, v172
	v_mul_f32_e32 v69, v69, v173
	v_cvt_pk_bf16_f32 v154, v66, v67
	v_cvt_pk_bf16_f32 v155, v68, v69
	v_mul_f32_e32 v170, 0xbfb8aa3b, v70
	v_mul_f32_e32 v171, 0xbfb8aa3b, v71
	v_mul_f32_e32 v172, 0xbfb8aa3b, v72
	v_mul_f32_e32 v173, 0xbfb8aa3b, v73
	v_exp_f32_e32 v170, v170
	v_exp_f32_e32 v171, v171
	v_exp_f32_e32 v172, v172
	v_exp_f32_e32 v173, v173
	v_add_f32_e32 v170, 1.0, v170
	v_add_f32_e32 v171, 1.0, v171
	v_add_f32_e32 v172, 1.0, v172
	v_add_f32_e32 v173, 1.0, v173
	v_rcp_f32_e32 v170, v170
	v_rcp_f32_e32 v171, v171
	v_rcp_f32_e32 v172, v172
	v_rcp_f32_e32 v173, v173
	s_nop 0
	v_mul_f32_e32 v70, v70, v170
	v_mul_f32_e32 v71, v71, v171
	v_mul_f32_e32 v72, v72, v172
	v_mul_f32_e32 v73, v73, v173
	v_cvt_pk_bf16_f32 v156, v70, v71
	v_cvt_pk_bf16_f32 v157, v72, v73
	global_store_dwordx4 v148, v[154:157], s[8:9]
	s_add_u32 s8, s8, 0xf000
	s_addc_u32 s9, s9, 0
	ds_write2_b32 v146, v50, v34 offset0:0 offset1:32
	ds_write2_b32 v146, v51, v35 offset0:68 offset1:100
	ds_write2_b32 v146, v52, v36 offset0:136 offset1:168
	ds_write2_b32 v146, v53, v37 offset0:204 offset1:236
	v_add_u32_e32 v146, 0x880, v146
	s_waitcnt lgkmcnt(8)
	v_mul_f32_e32 v170, 0xbfb8aa3b, v74
	v_mul_f32_e32 v171, 0xbfb8aa3b, v75
	v_mul_f32_e32 v172, 0xbfb8aa3b, v76
	v_mul_f32_e32 v173, 0xbfb8aa3b, v77
	v_exp_f32_e32 v170, v170
	v_exp_f32_e32 v171, v171
	v_exp_f32_e32 v172, v172
	v_exp_f32_e32 v173, v173
	v_add_f32_e32 v170, 1.0, v170
	v_add_f32_e32 v171, 1.0, v171
	v_add_f32_e32 v172, 1.0, v172
	v_add_f32_e32 v173, 1.0, v173
	v_rcp_f32_e32 v170, v170
	v_rcp_f32_e32 v171, v171
	v_rcp_f32_e32 v172, v172
	v_rcp_f32_e32 v173, v173
	s_nop 0
	v_mul_f32_e32 v74, v74, v170
	v_mul_f32_e32 v75, v75, v171
	v_mul_f32_e32 v76, v76, v172
	v_mul_f32_e32 v77, v77, v173
	v_cvt_pk_bf16_f32 v158, v74, v75
	v_cvt_pk_bf16_f32 v159, v76, v77
	v_mul_f32_e32 v170, 0xbfb8aa3b, v78
	v_mul_f32_e32 v171, 0xbfb8aa3b, v79
	v_mul_f32_e32 v172, 0xbfb8aa3b, v80
	v_mul_f32_e32 v173, 0xbfb8aa3b, v81
	v_exp_f32_e32 v170, v170
	v_exp_f32_e32 v171, v171
	v_exp_f32_e32 v172, v172
	v_exp_f32_e32 v173, v173
	v_add_f32_e32 v170, 1.0, v170
	v_add_f32_e32 v171, 1.0, v171
	v_add_f32_e32 v172, 1.0, v172
	v_add_f32_e32 v173, 1.0, v173
	v_rcp_f32_e32 v170, v170
	v_rcp_f32_e32 v171, v171
	v_rcp_f32_e32 v172, v172
	v_rcp_f32_e32 v173, v173
	s_nop 0
	v_mul_f32_e32 v78, v78, v170
	v_mul_f32_e32 v79, v79, v171
	v_mul_f32_e32 v80, v80, v172
	v_mul_f32_e32 v81, v81, v173
	v_cvt_pk_bf16_f32 v160, v78, v79
	v_cvt_pk_bf16_f32 v161, v80, v81
	global_store_dwordx4 v148, v[158:161], s[8:9]
	s_add_u32 s8, s8, 0xf000
	s_addc_u32 s9, s9, 0
	ds_write2_b32 v146, v54, v38 offset0:0 offset1:32
	ds_write2_b32 v146, v55, v39 offset0:68 offset1:100
	ds_write2_b32 v146, v56, v40 offset0:136 offset1:168
	ds_write2_b32 v146, v57, v41 offset0:204 offset1:236
	v_add_u32_e32 v146, 0x880, v146
	s_waitcnt lgkmcnt(10)
	v_mul_f32_e32 v170, 0xbfb8aa3b, v82
	v_mul_f32_e32 v171, 0xbfb8aa3b, v83
	v_mul_f32_e32 v172, 0xbfb8aa3b, v84
	v_mul_f32_e32 v173, 0xbfb8aa3b, v85
	v_exp_f32_e32 v170, v170
	v_exp_f32_e32 v171, v171
	v_exp_f32_e32 v172, v172
	v_exp_f32_e32 v173, v173
	v_add_f32_e32 v170, 1.0, v170
	v_add_f32_e32 v171, 1.0, v171
	v_add_f32_e32 v172, 1.0, v172
	v_add_f32_e32 v173, 1.0, v173
	v_rcp_f32_e32 v170, v170
	v_rcp_f32_e32 v171, v171
	v_rcp_f32_e32 v172, v172
	v_rcp_f32_e32 v173, v173
	s_nop 0
	v_mul_f32_e32 v82, v82, v170
	v_mul_f32_e32 v83, v83, v171
	v_mul_f32_e32 v84, v84, v172
	v_mul_f32_e32 v85, v85, v173
	v_cvt_pk_bf16_f32 v162, v82, v83
	v_cvt_pk_bf16_f32 v163, v84, v85
	v_mul_f32_e32 v170, 0xbfb8aa3b, v86
	v_mul_f32_e32 v171, 0xbfb8aa3b, v87
	v_mul_f32_e32 v172, 0xbfb8aa3b, v88
	v_mul_f32_e32 v173, 0xbfb8aa3b, v89
	v_exp_f32_e32 v170, v170
	v_exp_f32_e32 v171, v171
	v_exp_f32_e32 v172, v172
	v_exp_f32_e32 v173, v173
	v_add_f32_e32 v170, 1.0, v170
	v_add_f32_e32 v171, 1.0, v171
	v_add_f32_e32 v172, 1.0, v172
	v_add_f32_e32 v173, 1.0, v173
	v_rcp_f32_e32 v170, v170
	v_rcp_f32_e32 v171, v171
	v_rcp_f32_e32 v172, v172
	v_rcp_f32_e32 v173, v173
	s_nop 0
	v_mul_f32_e32 v86, v86, v170
	v_mul_f32_e32 v87, v87, v171
	v_mul_f32_e32 v88, v88, v172
	v_mul_f32_e32 v89, v89, v173
	v_cvt_pk_bf16_f32 v164, v86, v87
	v_cvt_pk_bf16_f32 v165, v88, v89
	global_store_dwordx4 v148, v[162:165], s[8:9]
	s_add_u32 s8, s8, 0xf000
	s_addc_u32 s9, s9, 0
	ds_write2_b32 v146, v58, v42 offset0:0 offset1:32
	ds_write2_b32 v146, v59, v43 offset0:68 offset1:100
	ds_write2_b32 v146, v60, v44 offset0:136 offset1:168
	ds_write2_b32 v146, v61, v45 offset0:204 offset1:236
	v_add_u32_e32 v146, 0x880, v146
	s_waitcnt lgkmcnt(12)
	v_mul_f32_e32 v170, 0xbfb8aa3b, v90
	v_mul_f32_e32 v171, 0xbfb8aa3b, v91
	v_mul_f32_e32 v172, 0xbfb8aa3b, v92
	v_mul_f32_e32 v173, 0xbfb8aa3b, v93
	v_exp_f32_e32 v170, v170
	v_exp_f32_e32 v171, v171
	v_exp_f32_e32 v172, v172
	v_exp_f32_e32 v173, v173
	v_add_f32_e32 v170, 1.0, v170
	v_add_f32_e32 v171, 1.0, v171
	v_add_f32_e32 v172, 1.0, v172
	v_add_f32_e32 v173, 1.0, v173
	v_rcp_f32_e32 v170, v170
	v_rcp_f32_e32 v171, v171
	v_rcp_f32_e32 v172, v172
	v_rcp_f32_e32 v173, v173
	s_nop 0
	v_mul_f32_e32 v90, v90, v170
	v_mul_f32_e32 v91, v91, v171
	v_mul_f32_e32 v92, v92, v172
	v_mul_f32_e32 v93, v93, v173
	v_cvt_pk_bf16_f32 v166, v90, v91
	v_cvt_pk_bf16_f32 v167, v92, v93
	v_mul_f32_e32 v170, 0xbfb8aa3b, v94
	v_mul_f32_e32 v171, 0xbfb8aa3b, v95
	v_mul_f32_e32 v172, 0xbfb8aa3b, v96
	v_mul_f32_e32 v173, 0xbfb8aa3b, v97
	v_exp_f32_e32 v170, v170
	v_exp_f32_e32 v171, v171
	v_exp_f32_e32 v172, v172
	v_exp_f32_e32 v173, v173
	v_add_f32_e32 v170, 1.0, v170
	v_add_f32_e32 v171, 1.0, v171
	v_add_f32_e32 v172, 1.0, v172
	v_add_f32_e32 v173, 1.0, v173
	v_rcp_f32_e32 v170, v170
	v_rcp_f32_e32 v171, v171
	v_rcp_f32_e32 v172, v172
	v_rcp_f32_e32 v173, v173
	s_nop 0
	v_mul_f32_e32 v94, v94, v170
	v_mul_f32_e32 v95, v95, v171
	v_mul_f32_e32 v96, v96, v172
	v_mul_f32_e32 v97, v97, v173
	v_cvt_pk_bf16_f32 v168, v94, v95
	v_cvt_pk_bf16_f32 v169, v96, v97
	global_store_dwordx4 v148, v[166:169], s[8:9]
	s_add_u32 s8, s8, 0xf000
	s_addc_u32 s9, s9, 0
	ds_write2_b32 v146, v62, v46 offset0:0 offset1:32
	ds_write2_b32 v146, v63, v47 offset0:68 offset1:100
	ds_write2_b32 v146, v64, v48 offset0:136 offset1:168
	ds_write2_b32 v146, v65, v49 offset0:204 offset1:236
	v_subrev_u32_e32 v146, 0x1980, v146
	ds_read_b128 v[34:37], v147
	ds_read_b128 v[38:41], v147 offset:16
	ds_read_b128 v[42:45], v147 offset:2176
	ds_read_b128 v[46:49], v147 offset:2192
	ds_read_b128 v[50:53], v147 offset:4352
	ds_read_b128 v[54:57], v147 offset:4368
	ds_read_b128 v[58:61], v147 offset:6528
	ds_read_b128 v[62:65], v147 offset:6544
	s_waitcnt lgkmcnt(6)
	v_mul_f32_e32 v170, 0xbfb8aa3b, v34
	v_mul_f32_e32 v171, 0xbfb8aa3b, v35
	v_mul_f32_e32 v172, 0xbfb8aa3b, v36
	v_mul_f32_e32 v173, 0xbfb8aa3b, v37
	v_exp_f32_e32 v170, v170
	v_exp_f32_e32 v171, v171
	v_exp_f32_e32 v172, v172
	v_exp_f32_e32 v173, v173
	v_add_f32_e32 v170, 1.0, v170
	v_add_f32_e32 v171, 1.0, v171
	v_add_f32_e32 v172, 1.0, v172
	v_add_f32_e32 v173, 1.0, v173
	v_rcp_f32_e32 v170, v170
	v_rcp_f32_e32 v171, v171
	v_rcp_f32_e32 v172, v172
	v_rcp_f32_e32 v173, v173
	s_nop 0
	v_mul_f32_e32 v34, v34, v170
	v_mul_f32_e32 v35, v35, v171
	v_mul_f32_e32 v36, v36, v172
	v_mul_f32_e32 v37, v37, v173
	v_cvt_pk_bf16_f32 v154, v34, v35
	v_cvt_pk_bf16_f32 v155, v36, v37
	v_mul_f32_e32 v170, 0xbfb8aa3b, v38
	v_mul_f32_e32 v171, 0xbfb8aa3b, v39
	v_mul_f32_e32 v172, 0xbfb8aa3b, v40
	v_mul_f32_e32 v173, 0xbfb8aa3b, v41
	v_exp_f32_e32 v170, v170
	v_exp_f32_e32 v171, v171
	v_exp_f32_e32 v172, v172
	v_exp_f32_e32 v173, v173
	v_add_f32_e32 v170, 1.0, v170
	v_add_f32_e32 v171, 1.0, v171
	v_add_f32_e32 v172, 1.0, v172
	v_add_f32_e32 v173, 1.0, v173
	v_rcp_f32_e32 v170, v170
	v_rcp_f32_e32 v171, v171
	v_rcp_f32_e32 v172, v172
	v_rcp_f32_e32 v173, v173
	s_nop 0
	v_mul_f32_e32 v38, v38, v170
	v_mul_f32_e32 v39, v39, v171
	v_mul_f32_e32 v40, v40, v172
	v_mul_f32_e32 v41, v41, v173
	v_cvt_pk_bf16_f32 v156, v38, v39
	v_cvt_pk_bf16_f32 v157, v40, v41
	global_store_dwordx4 v148, v[154:157], s[8:9]
	s_add_u32 s8, s8, 0xf000
	s_addc_u32 s9, s9, 0
	ds_write2_b32 v146, v18, v2 offset0:0 offset1:32
	ds_write2_b32 v146, v19, v3 offset0:68 offset1:100
	ds_write2_b32 v146, v20, v4 offset0:136 offset1:168
	ds_write2_b32 v146, v21, v5 offset0:204 offset1:236
	v_add_u32_e32 v146, 0x880, v146
	s_waitcnt lgkmcnt(8)
	v_mul_f32_e32 v170, 0xbfb8aa3b, v42
	v_mul_f32_e32 v171, 0xbfb8aa3b, v43
	v_mul_f32_e32 v172, 0xbfb8aa3b, v44
	v_mul_f32_e32 v173, 0xbfb8aa3b, v45
	v_exp_f32_e32 v170, v170
	v_exp_f32_e32 v171, v171
	v_exp_f32_e32 v172, v172
	v_exp_f32_e32 v173, v173
	v_add_f32_e32 v170, 1.0, v170
	v_add_f32_e32 v171, 1.0, v171
	v_add_f32_e32 v172, 1.0, v172
	v_add_f32_e32 v173, 1.0, v173
	v_rcp_f32_e32 v170, v170
	v_rcp_f32_e32 v171, v171
	v_rcp_f32_e32 v172, v172
	v_rcp_f32_e32 v173, v173
	s_nop 0
	v_mul_f32_e32 v42, v42, v170
	v_mul_f32_e32 v43, v43, v171
	v_mul_f32_e32 v44, v44, v172
	v_mul_f32_e32 v45, v45, v173
	v_cvt_pk_bf16_f32 v158, v42, v43
	v_cvt_pk_bf16_f32 v159, v44, v45
	v_mul_f32_e32 v170, 0xbfb8aa3b, v46
	v_mul_f32_e32 v171, 0xbfb8aa3b, v47
	v_mul_f32_e32 v172, 0xbfb8aa3b, v48
	v_mul_f32_e32 v173, 0xbfb8aa3b, v49
	v_exp_f32_e32 v170, v170
	v_exp_f32_e32 v171, v171
	v_exp_f32_e32 v172, v172
	v_exp_f32_e32 v173, v173
	v_add_f32_e32 v170, 1.0, v170
	v_add_f32_e32 v171, 1.0, v171
	v_add_f32_e32 v172, 1.0, v172
	v_add_f32_e32 v173, 1.0, v173
	v_rcp_f32_e32 v170, v170
	v_rcp_f32_e32 v171, v171
	v_rcp_f32_e32 v172, v172
	v_rcp_f32_e32 v173, v173
	s_nop 0
	v_mul_f32_e32 v46, v46, v170
	v_mul_f32_e32 v47, v47, v171
	v_mul_f32_e32 v48, v48, v172
	v_mul_f32_e32 v49, v49, v173
	v_cvt_pk_bf16_f32 v160, v46, v47
	v_cvt_pk_bf16_f32 v161, v48, v49
	global_store_dwordx4 v148, v[158:161], s[8:9]
	s_add_u32 s8, s8, 0xf000
	s_addc_u32 s9, s9, 0
	ds_write2_b32 v146, v22, v6 offset0:0 offset1:32
	ds_write2_b32 v146, v23, v7 offset0:68 offset1:100
	ds_write2_b32 v146, v24, v8 offset0:136 offset1:168
	ds_write2_b32 v146, v25, v9 offset0:204 offset1:236
	v_add_u32_e32 v146, 0x880, v146
	s_waitcnt lgkmcnt(10)
	v_mul_f32_e32 v170, 0xbfb8aa3b, v50
	v_mul_f32_e32 v171, 0xbfb8aa3b, v51
	v_mul_f32_e32 v172, 0xbfb8aa3b, v52
	v_mul_f32_e32 v173, 0xbfb8aa3b, v53
	v_exp_f32_e32 v170, v170
	v_exp_f32_e32 v171, v171
	v_exp_f32_e32 v172, v172
	v_exp_f32_e32 v173, v173
	v_add_f32_e32 v170, 1.0, v170
	v_add_f32_e32 v171, 1.0, v171
	v_add_f32_e32 v172, 1.0, v172
	v_add_f32_e32 v173, 1.0, v173
	v_rcp_f32_e32 v170, v170
	v_rcp_f32_e32 v171, v171
	v_rcp_f32_e32 v172, v172
	v_rcp_f32_e32 v173, v173
	s_nop 0
	v_mul_f32_e32 v50, v50, v170
	v_mul_f32_e32 v51, v51, v171
	v_mul_f32_e32 v52, v52, v172
	v_mul_f32_e32 v53, v53, v173
	v_cvt_pk_bf16_f32 v162, v50, v51
	v_cvt_pk_bf16_f32 v163, v52, v53
	v_mul_f32_e32 v170, 0xbfb8aa3b, v54
	v_mul_f32_e32 v171, 0xbfb8aa3b, v55
	v_mul_f32_e32 v172, 0xbfb8aa3b, v56
	v_mul_f32_e32 v173, 0xbfb8aa3b, v57
	v_exp_f32_e32 v170, v170
	v_exp_f32_e32 v171, v171
	v_exp_f32_e32 v172, v172
	v_exp_f32_e32 v173, v173
	v_add_f32_e32 v170, 1.0, v170
	v_add_f32_e32 v171, 1.0, v171
	v_add_f32_e32 v172, 1.0, v172
	v_add_f32_e32 v173, 1.0, v173
	v_rcp_f32_e32 v170, v170
	v_rcp_f32_e32 v171, v171
	v_rcp_f32_e32 v172, v172
	v_rcp_f32_e32 v173, v173
	s_nop 0
	v_mul_f32_e32 v54, v54, v170
	v_mul_f32_e32 v55, v55, v171
	v_mul_f32_e32 v56, v56, v172
	v_mul_f32_e32 v57, v57, v173
	v_cvt_pk_bf16_f32 v164, v54, v55
	v_cvt_pk_bf16_f32 v165, v56, v57
	global_store_dwordx4 v148, v[162:165], s[8:9]
	s_add_u32 s8, s8, 0xf000
	s_addc_u32 s9, s9, 0
	ds_write2_b32 v146, v26, v10 offset0:0 offset1:32
	ds_write2_b32 v146, v27, v11 offset0:68 offset1:100
	ds_write2_b32 v146, v28, v12 offset0:136 offset1:168
	ds_write2_b32 v146, v29, v13 offset0:204 offset1:236
	v_add_u32_e32 v146, 0x880, v146
	s_waitcnt lgkmcnt(12)
	v_mul_f32_e32 v170, 0xbfb8aa3b, v58
	v_mul_f32_e32 v171, 0xbfb8aa3b, v59
	v_mul_f32_e32 v172, 0xbfb8aa3b, v60
	v_mul_f32_e32 v173, 0xbfb8aa3b, v61
	v_exp_f32_e32 v170, v170
	v_exp_f32_e32 v171, v171
	v_exp_f32_e32 v172, v172
	v_exp_f32_e32 v173, v173
	v_add_f32_e32 v170, 1.0, v170
	v_add_f32_e32 v171, 1.0, v171
	v_add_f32_e32 v172, 1.0, v172
	v_add_f32_e32 v173, 1.0, v173
	v_rcp_f32_e32 v170, v170
	v_rcp_f32_e32 v171, v171
	v_rcp_f32_e32 v172, v172
	v_rcp_f32_e32 v173, v173
	s_nop 0
	v_mul_f32_e32 v58, v58, v170
	v_mul_f32_e32 v59, v59, v171
	v_mul_f32_e32 v60, v60, v172
	v_mul_f32_e32 v61, v61, v173
	v_cvt_pk_bf16_f32 v166, v58, v59
	v_cvt_pk_bf16_f32 v167, v60, v61
	v_mul_f32_e32 v170, 0xbfb8aa3b, v62
	v_mul_f32_e32 v171, 0xbfb8aa3b, v63
	v_mul_f32_e32 v172, 0xbfb8aa3b, v64
	v_mul_f32_e32 v173, 0xbfb8aa3b, v65
	v_exp_f32_e32 v170, v170
	v_exp_f32_e32 v171, v171
	v_exp_f32_e32 v172, v172
	v_exp_f32_e32 v173, v173
	v_add_f32_e32 v170, 1.0, v170
	v_add_f32_e32 v171, 1.0, v171
	v_add_f32_e32 v172, 1.0, v172
	v_add_f32_e32 v173, 1.0, v173
	v_rcp_f32_e32 v170, v170
	v_rcp_f32_e32 v171, v171
	v_rcp_f32_e32 v172, v172
	v_rcp_f32_e32 v173, v173
	s_nop 0
	v_mul_f32_e32 v62, v62, v170
	v_mul_f32_e32 v63, v63, v171
	v_mul_f32_e32 v64, v64, v172
	v_mul_f32_e32 v65, v65, v173
	v_cvt_pk_bf16_f32 v168, v62, v63
	v_cvt_pk_bf16_f32 v169, v64, v65
	global_store_dwordx4 v148, v[166:169], s[8:9]
	s_add_u32 s8, s8, 0xf000
	s_addc_u32 s9, s9, 0
	ds_write2_b32 v146, v30, v14 offset0:0 offset1:32
	ds_write2_b32 v146, v31, v15 offset0:68 offset1:100
	ds_write2_b32 v146, v32, v16 offset0:136 offset1:168
	ds_write2_b32 v146, v33, v17 offset0:204 offset1:236
	v_subrev_u32_e32 v146, 0x1980, v146
	ds_read_b128 v[2:5], v147
	ds_read_b128 v[6:9], v147 offset:16
	ds_read_b128 v[10:13], v147 offset:2176
	ds_read_b128 v[14:17], v147 offset:2192
	ds_read_b128 v[18:21], v147 offset:4352
	ds_read_b128 v[22:25], v147 offset:4368
	ds_read_b128 v[26:29], v147 offset:6528
	ds_read_b128 v[30:33], v147 offset:6544
	s_waitcnt lgkmcnt(0)
	s_barrier
	v_mul_f32_e32 v170, 0xbfb8aa3b, v2
	v_mul_f32_e32 v171, 0xbfb8aa3b, v3
	v_mul_f32_e32 v172, 0xbfb8aa3b, v4
	v_mul_f32_e32 v173, 0xbfb8aa3b, v5
	v_exp_f32_e32 v170, v170
	v_exp_f32_e32 v171, v171
	v_exp_f32_e32 v172, v172
	v_exp_f32_e32 v173, v173
	v_add_f32_e32 v170, 1.0, v170
	v_add_f32_e32 v171, 1.0, v171
	v_add_f32_e32 v172, 1.0, v172
	v_add_f32_e32 v173, 1.0, v173
	v_rcp_f32_e32 v170, v170
	v_rcp_f32_e32 v171, v171
	v_rcp_f32_e32 v172, v172
	v_rcp_f32_e32 v173, v173
	s_nop 0
	v_mul_f32_e32 v2, v2, v170
	v_mul_f32_e32 v3, v3, v171
	v_mul_f32_e32 v4, v4, v172
	v_mul_f32_e32 v5, v5, v173
	v_cvt_pk_bf16_f32 v154, v2, v3
	v_cvt_pk_bf16_f32 v155, v4, v5
	v_mul_f32_e32 v170, 0xbfb8aa3b, v6
	v_mul_f32_e32 v171, 0xbfb8aa3b, v7
	v_mul_f32_e32 v172, 0xbfb8aa3b, v8
	v_mul_f32_e32 v173, 0xbfb8aa3b, v9
	v_exp_f32_e32 v170, v170
	v_exp_f32_e32 v171, v171
	v_exp_f32_e32 v172, v172
	v_exp_f32_e32 v173, v173
	v_add_f32_e32 v170, 1.0, v170
	v_add_f32_e32 v171, 1.0, v171
	v_add_f32_e32 v172, 1.0, v172
	v_add_f32_e32 v173, 1.0, v173
	v_rcp_f32_e32 v170, v170
	v_rcp_f32_e32 v171, v171
	v_rcp_f32_e32 v172, v172
	v_rcp_f32_e32 v173, v173
	s_nop 0
	v_mul_f32_e32 v6, v6, v170
	v_mul_f32_e32 v7, v7, v171
	v_mul_f32_e32 v8, v8, v172
	v_mul_f32_e32 v9, v9, v173
	v_cvt_pk_bf16_f32 v156, v6, v7
	v_cvt_pk_bf16_f32 v157, v8, v9
	global_store_dwordx4 v148, v[154:157], s[8:9]
	s_add_u32 s8, s8, 0xf000
	s_addc_u32 s9, s9, 0
	v_mul_f32_e32 v170, 0xbfb8aa3b, v10
	v_mul_f32_e32 v171, 0xbfb8aa3b, v11
	v_mul_f32_e32 v172, 0xbfb8aa3b, v12
	v_mul_f32_e32 v173, 0xbfb8aa3b, v13
	v_exp_f32_e32 v170, v170
	v_exp_f32_e32 v171, v171
	v_exp_f32_e32 v172, v172
	v_exp_f32_e32 v173, v173
	v_add_f32_e32 v170, 1.0, v170
	v_add_f32_e32 v171, 1.0, v171
	v_add_f32_e32 v172, 1.0, v172
	v_add_f32_e32 v173, 1.0, v173
	v_rcp_f32_e32 v170, v170
	v_rcp_f32_e32 v171, v171
	v_rcp_f32_e32 v172, v172
	v_rcp_f32_e32 v173, v173
	s_nop 0
	v_mul_f32_e32 v10, v10, v170
	v_mul_f32_e32 v11, v11, v171
	v_mul_f32_e32 v12, v12, v172
	v_mul_f32_e32 v13, v13, v173
	v_cvt_pk_bf16_f32 v158, v10, v11
	v_cvt_pk_bf16_f32 v159, v12, v13
	v_mul_f32_e32 v170, 0xbfb8aa3b, v14
	v_mul_f32_e32 v171, 0xbfb8aa3b, v15
	v_mul_f32_e32 v172, 0xbfb8aa3b, v16
	v_mul_f32_e32 v173, 0xbfb8aa3b, v17
	v_exp_f32_e32 v170, v170
	v_exp_f32_e32 v171, v171
	v_exp_f32_e32 v172, v172
	v_exp_f32_e32 v173, v173
	v_add_f32_e32 v170, 1.0, v170
	v_add_f32_e32 v171, 1.0, v171
	v_add_f32_e32 v172, 1.0, v172
	v_add_f32_e32 v173, 1.0, v173
	v_rcp_f32_e32 v170, v170
	v_rcp_f32_e32 v171, v171
	v_rcp_f32_e32 v172, v172
	v_rcp_f32_e32 v173, v173
	s_nop 0
	v_mul_f32_e32 v14, v14, v170
	v_mul_f32_e32 v15, v15, v171
	v_mul_f32_e32 v16, v16, v172
	v_mul_f32_e32 v17, v17, v173
	v_cvt_pk_bf16_f32 v160, v14, v15
	v_cvt_pk_bf16_f32 v161, v16, v17
	global_store_dwordx4 v148, v[158:161], s[8:9]
	s_add_u32 s8, s8, 0xf000
	s_addc_u32 s9, s9, 0
	v_mul_f32_e32 v170, 0xbfb8aa3b, v18
	v_mul_f32_e32 v171, 0xbfb8aa3b, v19
	v_mul_f32_e32 v172, 0xbfb8aa3b, v20
	v_mul_f32_e32 v173, 0xbfb8aa3b, v21
	v_exp_f32_e32 v170, v170
	v_exp_f32_e32 v171, v171
	v_exp_f32_e32 v172, v172
	v_exp_f32_e32 v173, v173
	v_add_f32_e32 v170, 1.0, v170
	v_add_f32_e32 v171, 1.0, v171
	v_add_f32_e32 v172, 1.0, v172
	v_add_f32_e32 v173, 1.0, v173
	v_rcp_f32_e32 v170, v170
	v_rcp_f32_e32 v171, v171
	v_rcp_f32_e32 v172, v172
	v_rcp_f32_e32 v173, v173
	s_nop 0
	v_mul_f32_e32 v18, v18, v170
	v_mul_f32_e32 v19, v19, v171
	v_mul_f32_e32 v20, v20, v172
	v_mul_f32_e32 v21, v21, v173
	v_cvt_pk_bf16_f32 v162, v18, v19
	v_cvt_pk_bf16_f32 v163, v20, v21
	v_mul_f32_e32 v170, 0xbfb8aa3b, v22
	v_mul_f32_e32 v171, 0xbfb8aa3b, v23
	v_mul_f32_e32 v172, 0xbfb8aa3b, v24
	v_mul_f32_e32 v173, 0xbfb8aa3b, v25
	v_exp_f32_e32 v170, v170
	v_exp_f32_e32 v171, v171
	v_exp_f32_e32 v172, v172
	v_exp_f32_e32 v173, v173
	v_add_f32_e32 v170, 1.0, v170
	v_add_f32_e32 v171, 1.0, v171
	v_add_f32_e32 v172, 1.0, v172
	v_add_f32_e32 v173, 1.0, v173
	v_rcp_f32_e32 v170, v170
	v_rcp_f32_e32 v171, v171
	v_rcp_f32_e32 v172, v172
	v_rcp_f32_e32 v173, v173
	s_nop 0
	v_mul_f32_e32 v22, v22, v170
	v_mul_f32_e32 v23, v23, v171
	v_mul_f32_e32 v24, v24, v172
	v_mul_f32_e32 v25, v25, v173
	v_cvt_pk_bf16_f32 v164, v22, v23
	v_cvt_pk_bf16_f32 v165, v24, v25
	global_store_dwordx4 v148, v[162:165], s[8:9]
	s_add_u32 s8, s8, 0xf000
	s_addc_u32 s9, s9, 0
	v_mul_f32_e32 v170, 0xbfb8aa3b, v26
	v_mul_f32_e32 v171, 0xbfb8aa3b, v27
	v_mul_f32_e32 v172, 0xbfb8aa3b, v28
	v_mul_f32_e32 v173, 0xbfb8aa3b, v29
	v_exp_f32_e32 v170, v170
	v_exp_f32_e32 v171, v171
	v_exp_f32_e32 v172, v172
	v_exp_f32_e32 v173, v173
	v_add_f32_e32 v170, 1.0, v170
	v_add_f32_e32 v171, 1.0, v171
	v_add_f32_e32 v172, 1.0, v172
	v_add_f32_e32 v173, 1.0, v173
	v_rcp_f32_e32 v170, v170
	v_rcp_f32_e32 v171, v171
	v_rcp_f32_e32 v172, v172
	v_rcp_f32_e32 v173, v173
	s_nop 0
	v_mul_f32_e32 v26, v26, v170
	v_mul_f32_e32 v27, v27, v171
	v_mul_f32_e32 v28, v28, v172
	v_mul_f32_e32 v29, v29, v173
	v_cvt_pk_bf16_f32 v166, v26, v27
	v_cvt_pk_bf16_f32 v167, v28, v29
	v_mul_f32_e32 v170, 0xbfb8aa3b, v30
	v_mul_f32_e32 v171, 0xbfb8aa3b, v31
	v_mul_f32_e32 v172, 0xbfb8aa3b, v32
	v_mul_f32_e32 v173, 0xbfb8aa3b, v33
	v_exp_f32_e32 v170, v170
	v_exp_f32_e32 v171, v171
	v_exp_f32_e32 v172, v172
	v_exp_f32_e32 v173, v173
	v_add_f32_e32 v170, 1.0, v170
	v_add_f32_e32 v171, 1.0, v171
	v_add_f32_e32 v172, 1.0, v172
	v_add_f32_e32 v173, 1.0, v173
	v_rcp_f32_e32 v170, v170
	v_rcp_f32_e32 v171, v171
	v_rcp_f32_e32 v172, v172
	v_rcp_f32_e32 v173, v173
	s_nop 0
	v_mul_f32_e32 v30, v30, v170
	v_mul_f32_e32 v31, v31, v171
	v_mul_f32_e32 v32, v32, v172
	v_mul_f32_e32 v33, v33, v173
	v_cvt_pk_bf16_f32 v168, v30, v31
	v_cvt_pk_bf16_f32 v169, v32, v33
	global_store_dwordx4 v148, v[166:169], s[8:9]
	s_add_u32 s8, s8, 0xf000
	s_addc_u32 s9, s9, 0
	s_add_i32 s70, s70, s10
	s_cmp_lt_i32 s70, s71
	s_cbranch_scc0 .LBB0_209
	s_branch .LBB0_215
